# mixer-A loop: loop-back target line holds the barrier plus first body instructions; exit test evaluated under PV2
# baseline (speedup 1.0000x reference)
.Lattn_head_a:
	s_nop 0
	s_barrier

.Lattn_dma_done_a:
	v_exp_f32_e32 v172, v128
	v_exp_f32_e32 v170, v129
	v_exp_f32_e32 v176, v130
	v_exp_f32_e32 v168, v131
	v_exp_f32_e32 v182, v132
	v_exp_f32_e32 v178, v133
	v_exp_f32_e32 v188, v134
	v_exp_f32_e32 v174, v135
	v_exp_f32_e32 v192, v136
	v_exp_f32_e32 v186, v137
	v_exp_f32_e32 v194, v138
	v_exp_f32_e32 v180, v139
	v_exp_f32_e32 v196, v140
	v_exp_f32_e32 v190, v141
	v_exp_f32_e32 v198, v142
	v_exp_f32_e32 v184, v143
	v_cvt_pk_bf16_f32 v144, v173, v169
	v_cvt_pk_bf16_f32 v145, v177, v171
	v_cvt_pk_bf16_f32 v146, v183, v175
	v_cvt_pk_bf16_f32 v147, v189, v179
	v_cvt_pk_bf16_f32 v148, v193, v181
	v_cvt_pk_bf16_f32 v149, v195, v187
	v_cvt_pk_bf16_f32 v150, v197, v185
	v_cvt_pk_bf16_f32 v151, v199, v191
	v_cvt_pk_bf16_f32 v128, v172, v170
	v_cvt_pk_bf16_f32 v129, v176, v168
	v_cvt_pk_bf16_f32 v130, v182, v178
	v_cvt_pk_bf16_f32 v131, v188, v174
	v_cvt_pk_bf16_f32 v132, v192, v186
	v_cvt_pk_bf16_f32 v133, v194, v180
	v_cvt_pk_bf16_f32 v134, v196, v190
	v_cvt_pk_bf16_f32 v135, v198, v184
	v_add3_u32 v160, s7, v162, v160
	v_xad_u32 v252, v163, 64, s7
	v_add_u32_e32 v203, s7, v203
	v_add_u32_e32 v205, s7, v206
	ds_read_b64_tr_b16 v[136:137], v160 offset:32768
	ds_read_b64_tr_b16 v[138:139], v160 offset:34816
	ds_read_b64_tr_b16 v[140:141], v160 offset:36864
	ds_read_b64_tr_b16 v[142:143], v160 offset:38912
	ds_read_b64_tr_b16 v[152:153], v252 offset:32768
	ds_read_b64_tr_b16 v[154:155], v252 offset:34816
	ds_read_b64_tr_b16 v[156:157], v252 offset:36864
	ds_read_b64_tr_b16 v[158:159], v252 offset:38912
	ds_read_b64_tr_b16 v[208:209], v203 offset:32768
	ds_read_b64_tr_b16 v[210:211], v203 offset:34816
	ds_read_b64_tr_b16 v[212:213], v203 offset:36864
	ds_read_b64_tr_b16 v[214:215], v203 offset:38912
	ds_read_b64_tr_b16 v[216:217], v205 offset:32768
	ds_read_b64_tr_b16 v[218:219], v205 offset:34816
	ds_read_b64_tr_b16 v[220:221], v205 offset:36864
	ds_read_b64_tr_b16 v[222:223], v205 offset:38912
	s_waitcnt lgkmcnt(14)
	v_mfma_f32_32x32x16_bf16 v[64:79], v[144:147], v[136:139], v[64:79]
	v_mfma_f32_32x32x16_bf16 v[0:15], v[128:131], v[136:139], v[0:15]
	s_waitcnt lgkmcnt(10)
	v_mfma_f32_32x32x16_bf16 v[80:95], v[144:147], v[152:155], v[80:95]
	v_mfma_f32_32x32x16_bf16 v[16:31], v[128:131], v[152:155], v[16:31]
	s_waitcnt lgkmcnt(6)
	v_mfma_f32_32x32x16_bf16 v[96:111], v[144:147], v[208:211], v[96:111]
	v_mfma_f32_32x32x16_bf16 v[32:47], v[128:131], v[208:211], v[32:47]
	s_waitcnt lgkmcnt(2)
	v_mfma_f32_32x32x16_bf16 v[112:127], v[144:147], v[216:219], v[112:127]
	v_mfma_f32_32x32x16_bf16 v[48:63], v[128:131], v[216:219], v[48:63]
	v_mfma_f32_32x32x16_bf16 v[64:79], v[148:151], v[140:143], v[64:79]
	v_mfma_f32_32x32x16_bf16 v[0:15], v[132:135], v[140:143], v[0:15]
	v_mfma_f32_32x32x16_bf16 v[80:95], v[148:151], v[156:159], v[80:95]
	v_mfma_f32_32x32x16_bf16 v[16:31], v[132:135], v[156:159], v[16:31]
	v_mfma_f32_32x32x16_bf16 v[96:111], v[148:151], v[212:215], v[96:111]
	v_mfma_f32_32x32x16_bf16 v[32:47], v[132:135], v[212:215], v[32:47]
	s_waitcnt lgkmcnt(0)
	v_mfma_f32_32x32x16_bf16 v[112:127], v[148:151], v[220:223], v[112:127]
	v_mfma_f32_32x32x16_bf16 v[48:63], v[132:135], v[220:223], v[48:63]
	ds_read_b128 v[128:131], v207 offset:4096
	ds_read_b128 v[132:135], v224
	ds_read_b128 v[136:139], v225 offset:4096
	ds_read_b128 v[140:143], v226
	s_waitcnt lgkmcnt(2)
	v_mfma_f32_32x32x16_bf16 v[144:159], v[128:131], v[132:135], 0
	ds_read_b128 v[128:131], v227 offset:4096
	ds_read_b128 v[132:135], v228
	s_waitcnt lgkmcnt(2)
	v_mfma_f32_32x32x16_bf16 v[144:159], v[136:139], v[140:143], v[144:159]
	ds_read_b128 v[136:139], v230 offset:4096
	ds_read_b128 v[140:143], v232
	s_waitcnt lgkmcnt(2)
	v_mfma_f32_32x32x16_bf16 v[144:159], v[128:131], v[132:135], v[144:159]
	ds_read_b128 v[128:131], v207 offset:12288
	ds_read_b128 v[132:135], v224 offset:4096
	s_waitcnt lgkmcnt(2)
	v_mfma_f32_32x32x16_bf16 v[144:159], v[136:139], v[140:143], v[144:159]
	ds_read_b128 v[208:211], v225 offset:12288
	ds_read_b128 v[212:215], v226 offset:4096
	s_waitcnt lgkmcnt(2)
	v_mfma_f32_32x32x16_bf16 v[128:143], v[128:131], v[132:135], 0
	s_nop 7
	v_exp_f32_e32 v229, v144
	v_exp_f32_e32 v145, v145
	v_exp_f32_e32 v231, v146
	v_exp_f32_e32 v147, v147
	ds_read_b128 v[216:219], v227 offset:12288
	ds_read_b128 v[220:223], v228 offset:4096
	s_waitcnt lgkmcnt(2)
	v_mfma_f32_32x32x16_bf16 v[128:143], v[208:211], v[212:215], v[128:143]
	v_exp_f32_e32 v233, v148
	v_exp_f32_e32 v235, v149
	v_exp_f32_e32 v237, v150
	v_exp_f32_e32 v239, v151
	ds_read_b128 v[148:151], v230 offset:12288
	ds_read_b128 v[208:211], v232 offset:4096
	s_waitcnt lgkmcnt(2)
	v_mfma_f32_32x32x16_bf16 v[128:143], v[216:219], v[220:223], v[128:143]
	v_exp_f32_e32 v241, v152
	v_exp_f32_e32 v243, v153
	v_exp_f32_e32 v245, v154
	v_exp_f32_e32 v247, v155
	s_waitcnt lgkmcnt(0)
	v_mfma_f32_32x32x16_bf16 v[128:143], v[148:151], v[208:211], v[128:143]
	v_exp_f32_e32 v249, v156
	v_exp_f32_e32 v251, v157
	v_exp_f32_e32 v207, v158
	v_exp_f32_e32 v163, v159
	s_nop 7
	v_exp_f32_e32 v228, v128
	v_exp_f32_e32 v146, v129
	v_exp_f32_e32 v230, v130
	v_exp_f32_e32 v144, v131
	v_exp_f32_e32 v232, v132
	v_exp_f32_e32 v238, v133
	v_exp_f32_e32 v236, v134
	v_exp_f32_e32 v234, v135
	v_exp_f32_e32 v240, v136
	v_exp_f32_e32 v246, v137
	v_exp_f32_e32 v244, v138
	v_exp_f32_e32 v242, v139
	v_exp_f32_e32 v248, v140
	v_exp_f32_e32 v162, v141
	v_exp_f32_e32 v206, v142
	v_exp_f32_e32 v250, v143
	v_cvt_pk_bf16_f32 v148, v229, v145
	v_cvt_pk_bf16_f32 v149, v231, v147
	v_cvt_pk_bf16_f32 v150, v233, v235
	v_cvt_pk_bf16_f32 v151, v237, v239
	v_cvt_pk_bf16_f32 v152, v241, v243
	v_cvt_pk_bf16_f32 v153, v245, v247
	v_cvt_pk_bf16_f32 v154, v249, v251
	v_cvt_pk_bf16_f32 v155, v207, v163
	v_cvt_pk_bf16_f32 v128, v228, v146
	v_cvt_pk_bf16_f32 v129, v230, v144
	v_cvt_pk_bf16_f32 v130, v232, v238
	v_cvt_pk_bf16_f32 v131, v236, v234
	v_cvt_pk_bf16_f32 v132, v240, v246
	v_cvt_pk_bf16_f32 v133, v244, v242
	v_cvt_pk_bf16_f32 v134, v248, v162
	v_cvt_pk_bf16_f32 v135, v206, v250
	s_addk_i32 s5, 0x4000
	s_add_i32 s4, s4, 0x10000
	s_and_b32 s7, s5, 0x4000
	s_cmp_eq_u32 s4, 0x400000
	ds_read_b64_tr_b16 v[136:137], v160 offset:40960
	ds_read_b64_tr_b16 v[138:139], v160 offset:43008
	ds_read_b64_tr_b16 v[140:141], v160 offset:45056
	ds_read_b64_tr_b16 v[142:143], v160 offset:47104
	ds_read_b64_tr_b16 v[156:157], v252 offset:40960
	ds_read_b64_tr_b16 v[158:159], v252 offset:43008
	ds_read_b64_tr_b16 v[208:209], v252 offset:45056
	ds_read_b64_tr_b16 v[210:211], v252 offset:47104
	ds_read_b64_tr_b16 v[212:213], v203 offset:40960
	ds_read_b64_tr_b16 v[214:215], v203 offset:43008
	ds_read_b64_tr_b16 v[216:217], v203 offset:45056
	ds_read_b64_tr_b16 v[218:219], v203 offset:47104
	ds_read_b64_tr_b16 v[220:221], v205 offset:40960
	ds_read_b64_tr_b16 v[222:223], v205 offset:43008
	ds_read_b64_tr_b16 v[224:225], v205 offset:45056
	ds_read_b64_tr_b16 v[226:227], v205 offset:47104
	s_waitcnt lgkmcnt(14)
	v_mfma_f32_32x32x16_bf16 v[64:79], v[148:151], v[136:139], v[64:79]
	v_mfma_f32_32x32x16_bf16 v[0:15], v[128:131], v[136:139], v[0:15]
	s_waitcnt lgkmcnt(10)
	v_mfma_f32_32x32x16_bf16 v[80:95], v[148:151], v[156:159], v[80:95]
	v_mfma_f32_32x32x16_bf16 v[16:31], v[128:131], v[156:159], v[16:31]
	s_waitcnt lgkmcnt(6)
	v_mfma_f32_32x32x16_bf16 v[96:111], v[148:151], v[212:215], v[96:111]
	v_mfma_f32_32x32x16_bf16 v[32:47], v[128:131], v[212:215], v[32:47]
	s_waitcnt lgkmcnt(2)
	v_mfma_f32_32x32x16_bf16 v[112:127], v[148:151], v[220:223], v[112:127]
	v_mfma_f32_32x32x16_bf16 v[48:63], v[128:131], v[220:223], v[48:63]
	v_add_f32_e64 v128, v172, v176
	v_add_f32_e64 v129, v173, v177
	v_add_f32_e64 v130, v168, v170
	v_add_f32_e64 v131, v169, v171
	v_add_f32_e64 v128, v128, 0
	v_add_f32_e64 v129, v129, 0
	v_pk_add_f32 v[136:137], v[182:183], v[188:189]
	v_pk_add_f32 v[130:131], v[130:131], 0 op_sel_hi:[1,0]
	v_pk_add_f32 v[128:129], v[136:137], v[128:129]
	v_pk_add_f32 v[136:137], v[174:175], v[178:179]
	v_pk_add_f32 v[138:139], v[232:233], v[236:237]
	v_pk_add_f32 v[130:131], v[136:137], v[130:131]
	v_pk_add_f32 v[136:137], v[192:193], v[194:195]
	v_mfma_f32_32x32x16_bf16 v[64:79], v[152:155], v[140:143], v[64:79]
	v_add_f32_e64 v128, v136, v128
	v_add_f32_e64 v129, v137, v129
	v_add_f32_e64 v136, v180, v186
	v_add_f32_e64 v137, v181, v187
	v_add_f32_e64 v130, v136, v130
	v_add_f32_e64 v131, v137, v131
	v_pk_add_f32 v[136:137], v[196:197], v[198:199]
	s_nop 0
	v_pk_add_f32 v[128:129], v[136:137], v[128:129]
	v_pk_add_f32 v[136:137], v[184:185], v[190:191]
	v_mfma_f32_32x32x16_bf16 v[0:15], v[132:135], v[140:143], v[0:15]
	v_add_f32_e64 v130, v136, v130
	v_add_f32_e64 v131, v137, v131
	v_add_f32_e64 v136, v144, v146
	v_add_f32_e64 v137, v145, v147
	v_add_f32_e64 v128, v128, v130
	v_add_f32_e64 v129, v129, v131
	v_pk_add_f32 v[130:131], v[228:229], v[230:231]
	v_pk_add_f32 v[136:137], v[136:137], 0 op_sel_hi:[1,0]
	v_pk_add_f32 v[130:131], v[130:131], 0 op_sel_hi:[1,0]
	v_pk_add_f32 v[128:129], v[166:167], v[128:129]
	v_mfma_f32_32x32x16_bf16 v[80:95], v[152:155], v[208:211], v[80:95]
	v_add_f32_e64 v130, v138, v130
	v_add_f32_e64 v131, v139, v131
	v_add_f32_e64 v138, v234, v238
	v_add_f32_e64 v139, v235, v239
	v_add_f32_e64 v136, v138, v136
	v_add_f32_e64 v137, v139, v137
	v_pk_add_f32 v[138:139], v[240:241], v[244:245]
	s_nop 0
	v_pk_add_f32 v[130:131], v[138:139], v[130:131]
	v_mfma_f32_32x32x16_bf16 v[16:31], v[132:135], v[208:211], v[16:31]
	v_add_f32_e64 v138, v242, v246
	v_add_f32_e64 v139, v243, v247
	v_add_f32_e64 v136, v138, v136
	v_add_f32_e64 v137, v139, v137
	v_add_f32_e64 v138, v248, v206
	v_add_f32_e64 v139, v249, v207
	v_pk_add_f32 v[130:131], v[138:139], v[130:131]
	v_pk_add_f32 v[138:139], v[250:251], v[162:163]
	v_mfma_f32_32x32x16_bf16 v[96:111], v[152:155], v[216:219], v[96:111]
	v_add_f32_e64 v136, v138, v136
	v_add_f32_e64 v137, v139, v137
	v_add_f32_e64 v130, v130, v136
	v_add_f32_e64 v131, v131, v137
	v_add_f32_e64 v166, v128, v130
	v_add_f32_e64 v167, v129, v131
	v_mfma_f32_32x32x16_bf16 v[32:47], v[132:135], v[216:219], v[32:47]
	s_waitcnt lgkmcnt(0)
	v_mfma_f32_32x32x16_bf16 v[112:127], v[152:155], v[224:227], v[112:127]
	v_mfma_f32_32x32x16_bf16 v[48:63], v[132:135], v[224:227], v[48:63]
	s_waitcnt vmcnt(0)
	s_cbranch_scc0 .Lattn_head_a
	s_barrier
